# attention units: static balanced schedule per CU (heavy+light query-block pairs of each head type) instead of an atomic work queue with two barriers per unit
# speedup vs baseline: 1.0075x; 1.0017x over previous
; __device__ __forceinline__ int make_tid(int wave0) { int t = wave0 * 64 + (int)__builtin_amdgcn_mbcnt_hi(~0u, __builtin_amdgcn_mbcnt_lo(~0u, 0u)); asm volatile("" : "+v"(t)); return t; }
; #define LAS __attribute__((address_space(3)))
; __device__ __forceinline__ void attn_phase(LAS unsigned char* lds, int* counter, const bf16_t* __restrict__ P, const bf16_t* __restrict__ Qm, const bf16_t* __restrict__ Kmla, ...
;     LAS int* sunit = (LAS int*)(lds + MISC_OFF);
;     const int wid = wave0;
;     const int x0 = (int)((unsigned)__builtin_amdgcn_s_getreg((3 << 11) | 20) & 7u);
; #pragma nounroll
;     for (int xi = 0; xi < 8; ++xi) {
;     const int bq = (x0 + xi) & 7;
;     for (;;) {
;         const int tid = make_tid(wave0), lane = tid & 63, r32 = lane & 31, hi = lane >> 5;
;         __syncthreads();
;         if (tid == 0) *sunit = atomicAdd(counter + bq, 1);
;         __syncthreads();
;         const int u = __builtin_amdgcn_readfirstlane(*sunit);
;         if (u >= 256) break;
;         int r, qb;
;         if (u < 128) { qb = 15 - ((u & 63) >> 2); r = 64 + bq * 8 + (u >> 6) * 4 + (u & 3); }
;         else if (u < 192) { const int v_ = u - 128; qb = 15 - ((v_ & 31) >> 1); r = 32 + bq * 4 + (v_ >> 5) * 2 + (v_ & 1); }
;         else { const int v_ = u - 192; qb = 15 - ((v_ & 31) >> 1); r = bq * 4 + (v_ >> 5) * 2 + (v_ & 1); }
.LBB0_663:
	s_and_b64 vcc, exec, s[4:5]
	s_cbranch_vccz .LBB0_756
	v_readlane_b32 s12, v254, 44
	v_readlane_b32 s13, v254, 45
	s_and_b64 s[2:3], s[12:13], exec
	s_cselect_b32 s4, 8, 0
	s_lshl_b32 s2, s4, 2
	s_add_u32 s24, s8, s2
	s_addc_u32 s25, s9, 0
	s_add_u32 s26, s8, 0x146c1000
	s_addc_u32 s27, s9, 0
	s_add_u32 s28, s8, 0x15ec1000
	s_addc_u32 s29, s9, 0
	s_add_u32 s30, s8, 0x176c1000
	s_addc_u32 s31, s9, 0
	s_add_u32 s34, s8, 0x1c6c1000
	s_addc_u32 s35, s9, 0
	s_mov_b64 s[6:7], s[8:9]
	s_add_u32 s8, s6, 0x1c741000
	s_addc_u32 s9, s7, 0
	s_add_u32 s10, s6, 0x1c3c1000
	s_addc_u32 s11, s7, 0
	s_and_b64 s[2:3], s[12:13], exec
	s_cselect_b32 s12, 0x100, 0
	s_add_u32 s2, s6, s4
	s_addc_u32 s3, s7, 0
	global_load_dwordx2 v[0:1], v215, s[6:7] offset:3168
	global_load_dwordx2 v[180:181], v215, s[2:3] offset:256
	s_mov_b32 s13, 0
	v_readlane_b32 s68, v254, 7
	s_waitcnt vmcnt(1)
	v_lshl_add_u64 v[182:183], v[0:1], 0, s[12:13]
	s_getreg_b32 s12, hwreg(HW_REG_XCC_ID, 0, 4)
	v_readlane_b32 s2, v253, 58
	v_readlane_b32 s3, v254, 43
	s_nop 3
	s_and_b32 s3, s3, 7
	s_cmp_eq_u32 s2, 0x100
	s_cselect_b32 s12, s3, s12
	s_mov_b32 s2, 0
	s_nop 0
	v_writelane_b32 v255, s2, 62
	s_waitcnt vmcnt(0)
	v_sub_f32_e32 v181, 1.0, v181
	s_branch .LBB0_666
.Lsq_static:
	s_movk_i32 s4, 0x100
	s_cmp_lg_u32 s13, 0
	s_cbranch_scc1 .Lsq_done
	v_readlane_b32 s2, v255, 62
	s_nop 3
	s_cmp_gt_u32 s2, 7
	s_cbranch_scc1 .Lsq_done
	s_add_i32 s3, s2, 1
	s_nop 0
	v_writelane_b32 v255, s3, 62
	v_readlane_b32 s3, v254, 43
	s_nop 3
	s_lshr_b32 s3, s3, 3
	s_and_b32 s5, s2, 1
	s_lshr_b32 s2, s2, 1
	s_lshl_b32 s2, s2, 6
	s_sub_i32 s4, 63, s3
	s_cmp_lg_u32 s5, 0
	s_cselect_b32 s3, s4, s3
	s_add_i32 s4, s2, s3
.Lsq_done:
	s_mov_b64 s[2:3], -1
	s_branch .Lsq_join
.LBB0_665:
	s_add_i32 s13, s13, 1
	s_cmp_eq_u32 s13, 8
	s_cbranch_scc1 .LBB0_755

; __device__ __forceinline__ int make_tid(int wave0) { int t = wave0 * 64 + (int)__builtin_amdgcn_mbcnt_hi(~0u, __builtin_amdgcn_mbcnt_lo(~0u, 0u)); asm volatile("" : "+v"(t)); return t; }
; __device__ __forceinline__ void attn_phase(LAS unsigned char* lds, int* counter, const bf16_t* __restrict__ P, const bf16_t* __restrict__ Qm, const bf16_t* __restrict__ Kmla, ...
;     ...
;     for (;;) {
;         const int tid = make_tid(wave0), lane = tid & 63, r32 = lane & 31, hi = lane >> 5;
;         __syncthreads();
;         if (tid == 0) *sunit = atomicAdd(counter + bq, 1);
;         __syncthreads();
;         const int u = __builtin_amdgcn_readfirstlane(*sunit);
.LBB0_670:
	v_mov_b32_e32 v191, v246
	s_nop 0
	v_cmp_eq_u32_e32 vcc, 0, v191
	v_readlane_b32 s2, v253, 58
	s_nop 3
	s_cmp_eq_u32 s2, 0x100
	s_cbranch_scc1 .Lsq_static
	s_barrier
	s_and_saveexec_b64 s[2:3], vcc
	s_cbranch_execz .LBB0_674
	s_mov_b64 s[6:7], exec
	v_mbcnt_lo_u32_b32 v0, s6, 0
	v_mbcnt_hi_u32_b32 v0, s7, v0
	v_cmp_eq_u32_e32 vcc, 0, v0
	s_and_saveexec_b64 s[4:5], vcc
	s_cbranch_execz .LBB0_673
	s_bcnt1_i32_b64 s6, s[6:7]
	v_mov_b32_e32 v1, s6
	global_atomic_add v1, v215, v1, s[14:15] sc0

; __device__ __forceinline__ void attn_phase(LAS unsigned char* lds, int* counter, const bf16_t* __restrict__ P, const bf16_t* __restrict__ Qm, const bf16_t* __restrict__ Kmla, ...
;     ...
;         if (u >= 256) break;
;         int r, qb;
;         if (u < 128) { qb = 15 - ((u & 63) >> 2); r = 64 + bq * 8 + (u >> 6) * 4 + (u & 3); }
;         else if (u < 192) { const int v_ = u - 128; qb = 15 - ((v_ & 31) >> 1); r = 32 + bq * 4 + (v_ >> 5) * 2 + (v_ & 1); }
;         else { const int v_ = u - 192; qb = 15 - ((v_ & 31) >> 1); r = bq * 4 + (v_ >> 5) * 2 + (v_ & 1); }
.Lsq_join:
	s_cmpk_gt_i32 s4, 0xff
	s_cbranch_scc1 .LBB0_669
	s_cmpk_gt_i32 s4, 0x7f
	s_cbranch_scc0 .LBB0_681
	s_cmpk_gt_u32 s4, 0xbf
	s_cbranch_scc0 .LBB0_678
	s_add_i32 s2, s4, 0xffffff40
	s_lshr_b32 s2, s2, 4
	s_and_b32 s2, s2, 0xffffffe
	s_add_i32 s2, s2, s36
	s_and_b32 s3, s4, 1
	s_or_b32 s41, s2, s3
	s_mov_b64 s[2:3], 0
